# accumulator zeroing with v_mov_b64 (7 GEMM loops) + attention unit epilogue de-serialisation, on top of aligned loops + packed SwiGLU + gate epilogue
# baseline (speedup 1.0000x reference)
.LBB0_101:
	s_ashr_i32 s13, s12, 31
	v_cmp_lt_i64_e32 vcc, s[14:15], v[166:167]
	s_lshl_b64 s[14:15], s[12:13], 20
	v_readlane_b32 s16, v255, 34
	v_readlane_b32 s17, v255, 35
	s_add_u32 s14, s16, s14
	s_addc_u32 s15, s17, s15
	s_and_b64 s[16:17], vcc, exec
	s_cselect_b32 s13, s15, s21
	s_cselect_b32 s39, s14, s20
	s_ashr_i32 s11, s10, 31
	s_lshl_b64 s[16:17], s[10:11], 20
	s_add_u32 s16, s27, s16
	s_addc_u32 s17, s28, s17
	s_and_b64 s[24:25], vcc, exec
	s_cselect_b32 s11, s17, s23
	s_cselect_b32 s40, s16, s22
	s_add_u32 s20, s20, 0x80080
	s_addc_u32 s21, s21, 0
	s_add_u32 s41, s22, 0x100
	s_addc_u32 s42, s23, 0
	s_mov_b32 s43, -2
	v_mov_b64_e32 v[0:1], 0
	v_mov_b64_e32 v[2:3], 0
	v_mov_b64_e32 v[4:5], 0
	v_mov_b64_e32 v[6:7], 0
	v_mov_b64_e32 v[8:9], 0
	v_mov_b64_e32 v[10:11], 0
	v_mov_b64_e32 v[12:13], 0
	v_mov_b64_e32 v[14:15], 0
	v_mov_b64_e32 v[16:17], 0
	v_mov_b64_e32 v[18:19], 0
	v_mov_b64_e32 v[20:21], 0
	v_mov_b64_e32 v[22:23], 0
	v_mov_b64_e32 v[24:25], 0
	v_mov_b64_e32 v[26:27], 0
	v_mov_b64_e32 v[28:29], 0
	v_mov_b64_e32 v[30:31], 0
	v_mov_b64_e32 v[32:33], 0
	v_mov_b64_e32 v[34:35], 0
	v_mov_b64_e32 v[36:37], 0
	v_mov_b64_e32 v[38:39], 0
	v_mov_b64_e32 v[40:41], 0
	v_mov_b64_e32 v[42:43], 0
	v_mov_b64_e32 v[44:45], 0
	v_mov_b64_e32 v[46:47], 0
	v_mov_b64_e32 v[48:49], 0
	v_mov_b64_e32 v[50:51], 0
	v_mov_b64_e32 v[52:53], 0
	v_mov_b64_e32 v[54:55], 0
	v_mov_b64_e32 v[56:57], 0
	v_mov_b64_e32 v[58:59], 0
	v_mov_b64_e32 v[60:61], 0
	v_mov_b64_e32 v[62:63], 0
	v_mov_b64_e32 v[64:65], 0
	v_mov_b64_e32 v[66:67], 0
	v_mov_b64_e32 v[68:69], 0
	v_mov_b64_e32 v[70:71], 0
	v_mov_b64_e32 v[72:73], 0
	v_mov_b64_e32 v[74:75], 0
	v_mov_b64_e32 v[76:77], 0
	v_mov_b64_e32 v[78:79], 0
	v_mov_b64_e32 v[80:81], 0
	v_mov_b64_e32 v[82:83], 0
	v_mov_b64_e32 v[84:85], 0
	v_mov_b64_e32 v[86:87], 0
	v_mov_b64_e32 v[88:89], 0
	v_mov_b64_e32 v[90:91], 0
	v_mov_b64_e32 v[92:93], 0
	v_mov_b64_e32 v[94:95], 0
	v_mov_b64_e32 v[96:97], 0
	v_mov_b64_e32 v[98:99], 0
	v_mov_b64_e32 v[100:101], 0
	v_mov_b64_e32 v[102:103], 0
	v_mov_b64_e32 v[104:105], 0
	v_mov_b64_e32 v[106:107], 0
	v_mov_b64_e32 v[108:109], 0
	v_mov_b64_e32 v[110:111], 0
	v_mov_b64_e32 v[112:113], 0
	v_mov_b64_e32 v[114:115], 0
	v_mov_b64_e32 v[116:117], 0
	v_mov_b64_e32 v[118:119], 0
	v_mov_b64_e32 v[120:121], 0
	v_mov_b64_e32 v[122:123], 0
	v_mov_b64_e32 v[124:125], 0
	v_mov_b64_e32 v[126:127], 0
	.p2align 6

.LBB0_128:
	s_add_u32 s39, s16, 0x100
	s_addc_u32 s40, s17, 0
	s_mov_b32 s41, -2
	v_mov_b64_e32 v[0:1], 0
	v_mov_b64_e32 v[2:3], 0
	v_mov_b64_e32 v[4:5], 0
	v_mov_b64_e32 v[6:7], 0
	v_mov_b64_e32 v[8:9], 0
	v_mov_b64_e32 v[10:11], 0
	v_mov_b64_e32 v[12:13], 0
	v_mov_b64_e32 v[14:15], 0
	v_mov_b64_e32 v[16:17], 0
	v_mov_b64_e32 v[18:19], 0
	v_mov_b64_e32 v[20:21], 0
	v_mov_b64_e32 v[22:23], 0
	v_mov_b64_e32 v[24:25], 0
	v_mov_b64_e32 v[26:27], 0
	v_mov_b64_e32 v[28:29], 0
	v_mov_b64_e32 v[30:31], 0
	v_mov_b64_e32 v[32:33], 0
	v_mov_b64_e32 v[34:35], 0
	v_mov_b64_e32 v[36:37], 0
	v_mov_b64_e32 v[38:39], 0
	v_mov_b64_e32 v[40:41], 0
	v_mov_b64_e32 v[42:43], 0
	v_mov_b64_e32 v[44:45], 0
	v_mov_b64_e32 v[46:47], 0
	v_mov_b64_e32 v[48:49], 0
	v_mov_b64_e32 v[50:51], 0
	v_mov_b64_e32 v[52:53], 0
	v_mov_b64_e32 v[54:55], 0
	v_mov_b64_e32 v[56:57], 0
	v_mov_b64_e32 v[58:59], 0
	v_mov_b64_e32 v[60:61], 0
	v_mov_b64_e32 v[62:63], 0
	v_mov_b64_e32 v[64:65], 0
	v_mov_b64_e32 v[66:67], 0
	v_mov_b64_e32 v[68:69], 0
	v_mov_b64_e32 v[70:71], 0
	v_mov_b64_e32 v[72:73], 0
	v_mov_b64_e32 v[74:75], 0
	v_mov_b64_e32 v[76:77], 0
	v_mov_b64_e32 v[78:79], 0
	v_mov_b64_e32 v[80:81], 0
	v_mov_b64_e32 v[82:83], 0
	v_mov_b64_e32 v[84:85], 0
	v_mov_b64_e32 v[86:87], 0
	v_mov_b64_e32 v[88:89], 0
	v_mov_b64_e32 v[90:91], 0
	v_mov_b64_e32 v[92:93], 0
	v_mov_b64_e32 v[94:95], 0
	v_mov_b64_e32 v[96:97], 0
	v_mov_b64_e32 v[98:99], 0
	v_mov_b64_e32 v[100:101], 0
	v_mov_b64_e32 v[102:103], 0
	v_mov_b64_e32 v[104:105], 0
	v_mov_b64_e32 v[106:107], 0
	v_mov_b64_e32 v[108:109], 0
	v_mov_b64_e32 v[110:111], 0
	v_mov_b64_e32 v[112:113], 0
	v_mov_b64_e32 v[114:115], 0
	v_mov_b64_e32 v[116:117], 0
	v_mov_b64_e32 v[118:119], 0
	v_mov_b64_e32 v[120:121], 0
	v_mov_b64_e32 v[122:123], 0
	v_mov_b64_e32 v[124:125], 0
	v_mov_b64_e32 v[126:127], 0
	.p2align 6

.LBB0_142:
	s_ashr_i32 s13, s12, 31
	v_cmp_lt_i64_e32 vcc, s[14:15], v[170:171]
	s_lshl_b64 s[14:15], s[12:13], 20
	v_readlane_b32 s16, v255, 34
	v_readlane_b32 s17, v255, 35
	s_add_u32 s14, s16, s14
	s_addc_u32 s15, s17, s15
	s_and_b64 s[16:17], vcc, exec
	s_cselect_b32 s13, s15, s21
	s_cselect_b32 s39, s14, s20
	s_ashr_i32 s11, s10, 31
	s_lshl_b64 s[16:17], s[10:11], 20
	s_add_u32 s16, s26, s16
	s_addc_u32 s17, s27, s17
	s_and_b64 s[24:25], vcc, exec
	s_cselect_b32 s11, s17, s23
	s_cselect_b32 s40, s16, s22
	s_add_u32 s20, s20, 0x80080
	s_addc_u32 s21, s21, 0
	s_add_u32 s41, s22, 0x100
	s_addc_u32 s42, s23, 0
	s_mov_b32 s43, -2
	v_mov_b64_e32 v[0:1], 0
	v_mov_b64_e32 v[2:3], 0
	v_mov_b64_e32 v[4:5], 0
	v_mov_b64_e32 v[6:7], 0
	v_mov_b64_e32 v[8:9], 0
	v_mov_b64_e32 v[10:11], 0
	v_mov_b64_e32 v[12:13], 0
	v_mov_b64_e32 v[14:15], 0
	v_mov_b64_e32 v[16:17], 0
	v_mov_b64_e32 v[18:19], 0
	v_mov_b64_e32 v[20:21], 0
	v_mov_b64_e32 v[22:23], 0
	v_mov_b64_e32 v[24:25], 0
	v_mov_b64_e32 v[26:27], 0
	v_mov_b64_e32 v[28:29], 0
	v_mov_b64_e32 v[30:31], 0
	v_mov_b64_e32 v[32:33], 0
	v_mov_b64_e32 v[34:35], 0
	v_mov_b64_e32 v[36:37], 0
	v_mov_b64_e32 v[38:39], 0
	v_mov_b64_e32 v[40:41], 0
	v_mov_b64_e32 v[42:43], 0
	v_mov_b64_e32 v[44:45], 0
	v_mov_b64_e32 v[46:47], 0
	v_mov_b64_e32 v[48:49], 0
	v_mov_b64_e32 v[50:51], 0
	v_mov_b64_e32 v[52:53], 0
	v_mov_b64_e32 v[54:55], 0
	v_mov_b64_e32 v[56:57], 0
	v_mov_b64_e32 v[58:59], 0
	v_mov_b64_e32 v[60:61], 0
	v_mov_b64_e32 v[62:63], 0
	v_mov_b64_e32 v[64:65], 0
	v_mov_b64_e32 v[66:67], 0
	v_mov_b64_e32 v[68:69], 0
	v_mov_b64_e32 v[70:71], 0
	v_mov_b64_e32 v[72:73], 0
	v_mov_b64_e32 v[74:75], 0
	v_mov_b64_e32 v[76:77], 0
	v_mov_b64_e32 v[78:79], 0
	v_mov_b64_e32 v[80:81], 0
	v_mov_b64_e32 v[82:83], 0
	v_mov_b64_e32 v[84:85], 0
	v_mov_b64_e32 v[86:87], 0
	v_mov_b64_e32 v[88:89], 0
	v_mov_b64_e32 v[90:91], 0
	v_mov_b64_e32 v[92:93], 0
	v_mov_b64_e32 v[94:95], 0
	v_mov_b64_e32 v[96:97], 0
	v_mov_b64_e32 v[98:99], 0
	v_mov_b64_e32 v[100:101], 0
	v_mov_b64_e32 v[102:103], 0
	v_mov_b64_e32 v[104:105], 0
	v_mov_b64_e32 v[106:107], 0
	v_mov_b64_e32 v[108:109], 0
	v_mov_b64_e32 v[110:111], 0
	v_mov_b64_e32 v[112:113], 0
	v_mov_b64_e32 v[114:115], 0
	v_mov_b64_e32 v[116:117], 0
	v_mov_b64_e32 v[118:119], 0
	v_mov_b64_e32 v[120:121], 0
	v_mov_b64_e32 v[122:123], 0
	v_mov_b64_e32 v[124:125], 0
	v_mov_b64_e32 v[126:127], 0
	.p2align 6

.LBB0_166:
	s_ashr_i32 s13, s12, 31
	v_cmp_lt_i64_e32 vcc, s[14:15], v[166:167]
	s_lshl_b64 s[14:15], s[12:13], 20
	v_readlane_b32 s16, v255, 34
	v_readlane_b32 s17, v255, 35
	s_add_u32 s14, s16, s14
	s_addc_u32 s15, s17, s15
	s_and_b64 s[16:17], vcc, exec
	s_cselect_b32 s13, s15, s21
	s_cselect_b32 s41, s14, s20
	s_ashr_i32 s11, s10, 31
	s_lshl_b64 s[16:17], s[10:11], 20
	s_add_u32 s16, s29, s16
	s_addc_u32 s17, s30, s17
	s_and_b64 s[24:25], vcc, exec
	s_cselect_b32 s11, s17, s23
	s_cselect_b32 s42, s16, s22
	s_add_u32 s43, s22, 0x100
	s_addc_u32 s44, s23, 0
	s_mov_b32 s45, -2
	v_mov_b64_e32 v[0:1], 0
	v_mov_b64_e32 v[2:3], 0
	v_mov_b64_e32 v[4:5], 0
	v_mov_b64_e32 v[6:7], 0
	v_mov_b64_e32 v[8:9], 0
	v_mov_b64_e32 v[10:11], 0
	v_mov_b64_e32 v[12:13], 0
	v_mov_b64_e32 v[14:15], 0
	v_mov_b64_e32 v[16:17], 0
	v_mov_b64_e32 v[18:19], 0
	v_mov_b64_e32 v[20:21], 0
	v_mov_b64_e32 v[22:23], 0
	v_mov_b64_e32 v[24:25], 0
	v_mov_b64_e32 v[26:27], 0
	v_mov_b64_e32 v[28:29], 0
	v_mov_b64_e32 v[30:31], 0
	v_mov_b64_e32 v[32:33], 0
	v_mov_b64_e32 v[34:35], 0
	v_mov_b64_e32 v[36:37], 0
	v_mov_b64_e32 v[38:39], 0
	v_mov_b64_e32 v[40:41], 0
	v_mov_b64_e32 v[42:43], 0
	v_mov_b64_e32 v[44:45], 0
	v_mov_b64_e32 v[46:47], 0
	v_mov_b64_e32 v[48:49], 0
	v_mov_b64_e32 v[50:51], 0
	v_mov_b64_e32 v[52:53], 0
	v_mov_b64_e32 v[54:55], 0
	v_mov_b64_e32 v[56:57], 0
	v_mov_b64_e32 v[58:59], 0
	v_mov_b64_e32 v[60:61], 0
	v_mov_b64_e32 v[62:63], 0
	v_mov_b64_e32 v[64:65], 0
	v_mov_b64_e32 v[66:67], 0
	v_mov_b64_e32 v[68:69], 0
	v_mov_b64_e32 v[70:71], 0
	v_mov_b64_e32 v[72:73], 0
	v_mov_b64_e32 v[74:75], 0
	v_mov_b64_e32 v[76:77], 0
	v_mov_b64_e32 v[78:79], 0
	v_mov_b64_e32 v[80:81], 0
	v_mov_b64_e32 v[82:83], 0
	v_mov_b64_e32 v[84:85], 0
	v_mov_b64_e32 v[86:87], 0
	v_mov_b64_e32 v[88:89], 0
	v_mov_b64_e32 v[90:91], 0
	v_mov_b64_e32 v[92:93], 0
	v_mov_b64_e32 v[94:95], 0
	v_mov_b64_e32 v[96:97], 0
	v_mov_b64_e32 v[98:99], 0
	v_mov_b64_e32 v[100:101], 0
	v_mov_b64_e32 v[102:103], 0
	v_mov_b64_e32 v[104:105], 0
	v_mov_b64_e32 v[106:107], 0
	v_mov_b64_e32 v[108:109], 0
	v_mov_b64_e32 v[110:111], 0
	v_mov_b64_e32 v[112:113], 0
	v_mov_b64_e32 v[114:115], 0
	v_mov_b64_e32 v[116:117], 0
	v_mov_b64_e32 v[118:119], 0
	v_mov_b64_e32 v[120:121], 0
	v_mov_b64_e32 v[122:123], 0
	v_mov_b64_e32 v[124:125], 0
	v_mov_b64_e32 v[126:127], 0
	.p2align 6

.LBB0_302:
	s_ashr_i32 s21, s20, 31
	v_cmp_lt_i64_e32 vcc, s[22:23], v[174:175]
	s_lshl_b64 s[0:1], s[20:21], 20
	v_readlane_b32 s22, v255, 34
	v_readlane_b32 s23, v255, 35
	s_add_u32 s22, s22, s0
	s_addc_u32 s23, s23, s1
	s_and_b64 s[0:1], vcc, exec
	s_cselect_b32 s0, s23, s13
	s_cselect_b32 s1, s22, s12
	s_ashr_i32 s19, s18, 31
	s_lshl_b64 s[24:25], s[18:19], 20
	s_add_u32 s24, s36, s24
	s_addc_u32 s25, s37, s25
	s_and_b64 s[30:31], vcc, exec
	s_cselect_b32 s11, s25, s29
	s_cselect_b32 s19, s24, s28
	s_add_u32 s12, s12, 0x80080
	s_addc_u32 s13, s13, 0
	s_add_u32 s21, s28, 0x100
	s_addc_u32 s46, s29, 0
	s_mov_b32 s47, -2
	v_mov_b64_e32 v[0:1], 0
	v_mov_b64_e32 v[2:3], 0
	v_mov_b64_e32 v[4:5], 0
	v_mov_b64_e32 v[6:7], 0
	v_mov_b64_e32 v[8:9], 0
	v_mov_b64_e32 v[10:11], 0
	v_mov_b64_e32 v[12:13], 0
	v_mov_b64_e32 v[14:15], 0
	v_mov_b64_e32 v[16:17], 0
	v_mov_b64_e32 v[18:19], 0
	v_mov_b64_e32 v[20:21], 0
	v_mov_b64_e32 v[22:23], 0
	v_mov_b64_e32 v[24:25], 0
	v_mov_b64_e32 v[26:27], 0
	v_mov_b64_e32 v[28:29], 0
	v_mov_b64_e32 v[30:31], 0
	v_mov_b64_e32 v[32:33], 0
	v_mov_b64_e32 v[34:35], 0
	v_mov_b64_e32 v[36:37], 0
	v_mov_b64_e32 v[38:39], 0
	v_mov_b64_e32 v[40:41], 0
	v_mov_b64_e32 v[42:43], 0
	v_mov_b64_e32 v[44:45], 0
	v_mov_b64_e32 v[46:47], 0
	v_mov_b64_e32 v[48:49], 0
	v_mov_b64_e32 v[50:51], 0
	v_mov_b64_e32 v[52:53], 0
	v_mov_b64_e32 v[54:55], 0
	v_mov_b64_e32 v[56:57], 0
	v_mov_b64_e32 v[58:59], 0
	v_mov_b64_e32 v[60:61], 0
	v_mov_b64_e32 v[62:63], 0
	v_mov_b64_e32 v[64:65], 0
	v_mov_b64_e32 v[66:67], 0
	v_mov_b64_e32 v[68:69], 0
	v_mov_b64_e32 v[70:71], 0
	v_mov_b64_e32 v[72:73], 0
	v_mov_b64_e32 v[74:75], 0
	v_mov_b64_e32 v[76:77], 0
	v_mov_b64_e32 v[78:79], 0
	v_mov_b64_e32 v[80:81], 0
	v_mov_b64_e32 v[82:83], 0
	v_mov_b64_e32 v[84:85], 0
	v_mov_b64_e32 v[86:87], 0
	v_mov_b64_e32 v[88:89], 0
	v_mov_b64_e32 v[90:91], 0
	v_mov_b64_e32 v[92:93], 0
	v_mov_b64_e32 v[94:95], 0
	v_mov_b64_e32 v[96:97], 0
	v_mov_b64_e32 v[98:99], 0
	v_mov_b64_e32 v[100:101], 0
	v_mov_b64_e32 v[102:103], 0
	v_mov_b64_e32 v[104:105], 0
	v_mov_b64_e32 v[106:107], 0
	v_mov_b64_e32 v[108:109], 0
	v_mov_b64_e32 v[110:111], 0
	v_mov_b64_e32 v[112:113], 0
	v_mov_b64_e32 v[114:115], 0
	v_mov_b64_e32 v[116:117], 0
	v_mov_b64_e32 v[118:119], 0
	v_mov_b64_e32 v[120:121], 0
	v_mov_b64_e32 v[122:123], 0
	v_mov_b64_e32 v[124:125], 0
	v_mov_b64_e32 v[126:127], 0
	.p2align 6

.LBB0_483:
	s_add_u32 s43, s22, 0x100
	s_addc_u32 s44, s23, 0
	s_mov_b32 s45, -2
	v_mov_b64_e32 v[0:1], 0
	v_mov_b64_e32 v[2:3], 0
	v_mov_b64_e32 v[4:5], 0
	v_mov_b64_e32 v[6:7], 0
	v_mov_b64_e32 v[8:9], 0
	v_mov_b64_e32 v[10:11], 0
	v_mov_b64_e32 v[12:13], 0
	v_mov_b64_e32 v[14:15], 0
	v_mov_b64_e32 v[16:17], 0
	v_mov_b64_e32 v[18:19], 0
	v_mov_b64_e32 v[20:21], 0
	v_mov_b64_e32 v[22:23], 0
	v_mov_b64_e32 v[24:25], 0
	v_mov_b64_e32 v[26:27], 0
	v_mov_b64_e32 v[28:29], 0
	v_mov_b64_e32 v[30:31], 0
	v_mov_b64_e32 v[32:33], 0
	v_mov_b64_e32 v[34:35], 0
	v_mov_b64_e32 v[36:37], 0
	v_mov_b64_e32 v[38:39], 0
	v_mov_b64_e32 v[40:41], 0
	v_mov_b64_e32 v[42:43], 0
	v_mov_b64_e32 v[44:45], 0
	v_mov_b64_e32 v[46:47], 0
	v_mov_b64_e32 v[48:49], 0
	v_mov_b64_e32 v[50:51], 0
	v_mov_b64_e32 v[52:53], 0
	v_mov_b64_e32 v[54:55], 0
	v_mov_b64_e32 v[56:57], 0
	v_mov_b64_e32 v[58:59], 0
	v_mov_b64_e32 v[60:61], 0
	v_mov_b64_e32 v[62:63], 0
	v_mov_b64_e32 v[64:65], 0
	v_mov_b64_e32 v[66:67], 0
	v_mov_b64_e32 v[68:69], 0
	v_mov_b64_e32 v[70:71], 0
	v_mov_b64_e32 v[72:73], 0
	v_mov_b64_e32 v[74:75], 0
	v_mov_b64_e32 v[76:77], 0
	v_mov_b64_e32 v[78:79], 0
	v_mov_b64_e32 v[80:81], 0
	v_mov_b64_e32 v[82:83], 0
	v_mov_b64_e32 v[84:85], 0
	v_mov_b64_e32 v[86:87], 0
	v_mov_b64_e32 v[88:89], 0
	v_mov_b64_e32 v[90:91], 0
	v_mov_b64_e32 v[92:93], 0
	v_mov_b64_e32 v[94:95], 0
	v_mov_b64_e32 v[96:97], 0
	v_mov_b64_e32 v[98:99], 0
	v_mov_b64_e32 v[100:101], 0
	v_mov_b64_e32 v[102:103], 0
	v_mov_b64_e32 v[104:105], 0
	v_mov_b64_e32 v[106:107], 0
	v_mov_b64_e32 v[108:109], 0
	v_mov_b64_e32 v[110:111], 0
	v_mov_b64_e32 v[112:113], 0
	v_mov_b64_e32 v[114:115], 0
	v_mov_b64_e32 v[116:117], 0
	v_mov_b64_e32 v[118:119], 0
	v_mov_b64_e32 v[120:121], 0
	v_mov_b64_e32 v[122:123], 0
	v_mov_b64_e32 v[124:125], 0
	v_mov_b64_e32 v[126:127], 0
	.p2align 6
